# prefetch first four RMS row-sum loads before the K-loop in the in-proj and up GEMM epilogues; counted wait for the rest
# baseline (speedup 1.0000x reference)
.LBB0_79:
	s_ashr_i32 s47, s46, 31
	s_lshl_b64 s[4:5], s[46:47], 20
	v_readlane_b32 s48, v255, 14
	v_readlane_b32 s49, v255, 15
	s_add_u32 s48, s48, s4
	s_addc_u32 s49, s49, s5
	s_and_b64 s[4:5], s[38:39], exec
	s_cselect_b32 s4, s49, s57
	s_cselect_b32 s5, s48, s56
	s_ashr_i32 s45, s44, 31
	s_lshl_b64 s[50:51], s[44:45], 20
	s_add_u32 s50, s1, s50
	s_addc_u32 s51, s2, s51
	s_and_b64 s[58:59], s[38:39], exec
	s_cselect_b32 s45, s51, s55
	s_cselect_b32 s47, s50, s54
	s_add_u32 s62, s54, 0x100
	s_addc_u32 s63, s55, 0
	s_add_u32 s54, s56, 0x80080
	v_mov_b32_e32 v6, 0
	s_addc_u32 s55, s57, 0
	s_mov_b32 s64, -2
	v_mov_b32_e32 v7, v6
	v_mov_b32_e32 v8, v6
	v_mov_b32_e32 v9, v6
	v_mov_b32_e32 v10, v6
	v_mov_b32_e32 v11, v6
	v_mov_b32_e32 v12, v6
	v_mov_b32_e32 v13, v6
	v_mov_b32_e32 v22, v6
	v_mov_b32_e32 v23, v6
	v_mov_b32_e32 v24, v6
	v_mov_b32_e32 v25, v6
	v_mov_b32_e32 v26, v6
	v_mov_b32_e32 v27, v6
	v_mov_b32_e32 v28, v6
	v_mov_b32_e32 v29, v6
	v_mov_b32_e32 v38, v6
	v_mov_b32_e32 v39, v6
	v_mov_b32_e32 v40, v6
	v_mov_b32_e32 v41, v6
	s_waitcnt vmcnt(0)
	v_mov_b32_e32 v42, v6
	v_mov_b32_e32 v43, v6
	v_mov_b32_e32 v44, v6
	v_mov_b32_e32 v45, v6
	v_mov_b32_e32 v54, v6
	v_mov_b32_e32 v55, v6
	v_mov_b32_e32 v56, v6
	v_mov_b32_e32 v57, v6
	v_mov_b32_e32 v58, v6
	v_mov_b32_e32 v59, v6
	v_mov_b32_e32 v60, v6
	v_mov_b32_e32 v61, v6
	v_mov_b32_e32 v14, v6
	v_mov_b32_e32 v15, v6
	v_mov_b32_e32 v16, v6
	v_mov_b32_e32 v17, v6
	v_mov_b32_e32 v18, v6
	v_mov_b32_e32 v19, v6
	v_mov_b32_e32 v20, v6
	v_mov_b32_e32 v21, v6
	v_mov_b32_e32 v30, v6
	v_mov_b32_e32 v31, v6
	v_mov_b32_e32 v32, v6
	v_mov_b32_e32 v33, v6
	v_mov_b32_e32 v34, v6
	v_mov_b32_e32 v35, v6
	v_mov_b32_e32 v36, v6
	v_mov_b32_e32 v37, v6
	v_mov_b32_e32 v46, v6
	v_mov_b32_e32 v47, v6
	v_mov_b32_e32 v48, v6
	v_mov_b32_e32 v49, v6
	v_mov_b32_e32 v50, v6
	v_mov_b32_e32 v51, v6
	v_mov_b32_e32 v52, v6
	v_mov_b32_e32 v53, v6
	v_mov_b32_e32 v62, v6
	v_mov_b32_e32 v63, v6
	v_mov_b32_e32 v64, v6
	v_mov_b32_e32 v65, v6
	v_mov_b32_e32 v66, v6
	v_mov_b32_e32 v67, v6
	v_mov_b32_e32 v68, v6
	v_mov_b32_e32 v69, v6
	v_mov_b32_e32 v70, v6
	v_mov_b32_e32 v71, v6
	v_mov_b32_e32 v72, v6
	v_mov_b32_e32 v73, v6
	v_mov_b32_e32 v74, v6
	v_mov_b32_e32 v75, v6
	v_mov_b32_e32 v76, v6
	v_mov_b32_e32 v77, v6
	v_mov_b32_e32 v86, v6
	v_mov_b32_e32 v87, v6
	v_mov_b32_e32 v88, v6
	v_mov_b32_e32 v89, v6
	v_mov_b32_e32 v90, v6
	v_mov_b32_e32 v91, v6
	v_mov_b32_e32 v92, v6
	v_mov_b32_e32 v93, v6
	v_mov_b32_e32 v102, v6
	v_mov_b32_e32 v103, v6
	v_mov_b32_e32 v104, v6
	v_mov_b32_e32 v105, v6
	v_mov_b32_e32 v106, v6
	v_mov_b32_e32 v107, v6
	v_mov_b32_e32 v108, v6
	v_mov_b32_e32 v109, v6
	v_mov_b32_e32 v118, v6
	v_mov_b32_e32 v119, v6
	v_mov_b32_e32 v120, v6
	v_mov_b32_e32 v121, v6
	v_mov_b32_e32 v122, v6
	v_mov_b32_e32 v123, v6
	v_mov_b32_e32 v124, v6
	v_mov_b32_e32 v125, v6
	v_mov_b32_e32 v78, v6
	v_mov_b32_e32 v79, v6
	v_mov_b32_e32 v80, v6
	v_mov_b32_e32 v81, v6
	v_mov_b32_e32 v82, v6
	v_mov_b32_e32 v83, v6
	v_mov_b32_e32 v84, v6
	v_mov_b32_e32 v85, v6
	v_mov_b32_e32 v94, v6
	v_mov_b32_e32 v95, v6
	v_mov_b32_e32 v96, v6
	v_mov_b32_e32 v97, v6
	v_mov_b32_e32 v98, v6
	v_mov_b32_e32 v99, v6
	v_mov_b32_e32 v100, v6
	v_mov_b32_e32 v101, v6
	v_mov_b32_e32 v110, v6
	v_mov_b32_e32 v111, v6
	v_mov_b32_e32 v112, v6
	v_mov_b32_e32 v113, v6
	v_mov_b32_e32 v114, v6
	v_mov_b32_e32 v115, v6
	v_mov_b32_e32 v116, v6
	v_mov_b32_e32 v117, v6
	v_mov_b32_e32 v126, v6
	v_mov_b32_e32 v127, v6
	v_mov_b32_e32 v128, v6
	v_mov_b32_e32 v129, v6
	v_mov_b32_e32 v130, v6
	v_mov_b32_e32 v131, v6
	v_mov_b32_e32 v132, v6
	v_mov_b32_e32 v133, v6
	v_lshl_add_u32 v2, s52, 8, v168
	v_ashrrev_i32_e32 v3, 31, v2
	v_lshl_add_u64 v[2:3], v[2:3], 3, s[40:41]
	global_load_dwordx2 v[246:247], v[2:3], off
	global_load_dwordx2 v[248:249], v[2:3], off offset:128
	global_load_dwordx2 v[250:251], v[2:3], off offset:256
	global_load_dwordx2 v[252:253], v[2:3], off offset:384
	s_nop 1
	v_mov_b32_e32 v2, 0
	v_mov_b32_e32 v3, 0

.LBB0_83:
	v_lshl_add_u32 v146, s52, 8, v168
	v_ashrrev_i32_e32 v147, 31, v146
	v_lshl_add_u64 v[144:145], v[146:147], 3, s[40:41]
	v_mov_b64_e32 v[172:173], v[246:247]
	v_mov_b64_e32 v[164:165], v[248:249]
	v_mov_b64_e32 v[160:161], v[250:251]
	v_mov_b64_e32 v[154:155], v[252:253]
	global_load_dwordx2 v[152:153], v[144:145], off offset:1024
	global_load_dwordx2 v[150:151], v[144:145], off offset:1152
	global_load_dwordx2 v[148:149], v[144:145], off offset:1280
	s_nop 0
	global_load_dwordx2 v[144:145], v[144:145], off offset:1408
	v_lshl_or_b32 v158, s61, 8, v170
	v_or_b32_e32 v166, 16, v146
	v_or_b32_e32 v162, 32, v146
	v_or_b32_e32 v156, 48, v146
	v_ashrrev_i32_e32 v159, 31, v158
	v_lshlrev_b64 v[146:147], 14, v[146:147]
	v_lshl_add_u64 v[146:147], s[36:37], 0, v[146:147]
	v_lshlrev_b64 v[158:159], 1, v[158:159]
	v_lshl_add_u64 v[146:147], v[146:147], 0, v[158:159]
	v_ashrrev_i32_e32 v167, 31, v166
	v_ashrrev_i32_e32 v163, 31, v162
	v_ashrrev_i32_e32 v157, 31, v156
	s_mov_b64 s[4:5], 0x200000
	v_ffbh_u32_e32 v174, v173
	v_min_u32_e32 v174, 32, v174
	v_lshlrev_b64 v[172:173], v174, v[172:173]
	v_min_u32_e32 v172, 1, v172
	v_or_b32_e32 v172, v173, v172
	v_cvt_f32_u32_e32 v172, v172
	v_sub_u32_e32 v173, 32, v174
	v_ldexp_f32 v172, v172, v173
	v_fmamk_f32 v172, v172, 0x2e000000, v1
	v_rsq_f32_e32 v172, v172
	s_nop 0
	v_pk_mul_f32 v[126:127], v[126:127], v[172:173] op_sel_hi:[1,0]
	v_pk_mul_f32 v[130:131], v[130:131], v[172:173] op_sel_hi:[1,0]
	v_pk_mul_f32 v[128:129], v[128:129], v[172:173] op_sel_hi:[1,0]
	v_max_f32_e32 v126, 0, v126
	v_pk_mul_f32 v[132:133], v[132:133], v[172:173] op_sel_hi:[1,0]
	v_mul_f32_e32 v173, v126, v126
	v_max_f32_e32 v126, 0, v131
	v_max_f32_e32 v127, 0, v127
	v_max_f32_e32 v128, 0, v128
	v_max_f32_e32 v130, 0, v130
	v_mul_f32_e32 v126, v126, v126
	v_mul_f32_e32 v131, v127, v127
	v_max_f32_e32 v127, 0, v132
	v_mul_f32_e32 v132, v128, v128
	v_max_f32_e32 v128, 0, v133
	v_max_f32_e32 v129, 0, v129
	v_pk_mul_f32 v[120:121], v[120:121], v[172:173] op_sel_hi:[1,0]
	v_pk_mul_f32 v[118:119], v[118:119], v[172:173] op_sel_hi:[1,0]
	v_mul_f32_e32 v130, v130, v130
	v_mul_f32_e32 v127, v127, v127
	v_mul_f32_e32 v128, v128, v128
	v_mul_f32_e32 v129, v129, v129
	v_cvt_pk_bf16_f32 v126, v130, v126
	v_pk_mul_f32 v[124:125], v[124:125], v[172:173] op_sel_hi:[1,0]
	v_pk_mul_f32 v[122:123], v[122:123], v[172:173] op_sel_hi:[1,0]
	v_max_f32_e32 v118, 0, v118
	v_max_f32_e32 v119, 0, v119
	v_max_f32_e32 v120, 0, v120
	v_cvt_pk_bf16_f32 v127, v127, v128
	v_cvt_pk_bf16_f32 v128, v173, v131
	v_cvt_pk_bf16_f32 v129, v132, v129
	global_store_dwordx4 v[146:147], v[126:129], off
	v_max_f32_e32 v122, 0, v122
	v_max_f32_e32 v121, 0, v121
	v_mul_f32_e32 v126, v118, v118
	v_max_f32_e32 v118, 0, v123
	v_mul_f32_e32 v123, v119, v119
	v_max_f32_e32 v119, 0, v124
	v_mul_f32_e32 v124, v120, v120
	v_max_f32_e32 v120, 0, v125
	v_mul_f32_e32 v118, v118, v118
	v_mul_f32_e32 v119, v119, v119
	v_mul_f32_e32 v120, v120, v120
	v_mul_f32_e32 v122, v122, v122
	v_mul_f32_e32 v121, v121, v121
	v_cvt_pk_bf16_f32 v118, v122, v118
	v_cvt_pk_bf16_f32 v119, v119, v120
	v_cvt_pk_bf16_f32 v120, v126, v123
	v_cvt_pk_bf16_f32 v121, v124, v121
	global_store_dwordx4 v[146:147], v[118:121], off offset:256
	s_nop 1
	v_ffbh_u32_e32 v120, v165
	v_min_u32_e32 v122, 32, v120
	v_lshlrev_b64 v[120:121], v122, v[164:165]
	v_min_u32_e32 v120, 1, v120
	v_or_b32_e32 v120, v121, v120
	v_cvt_f32_u32_e32 v120, v120
	v_sub_u32_e32 v121, 32, v122
	v_lshlrev_b64 v[118:119], 14, v[166:167]
	v_lshl_add_u64 v[118:119], s[36:37], 0, v[118:119]
	v_ldexp_f32 v120, v120, v121
	v_fmamk_f32 v120, v120, 0x2e000000, v1
	v_rsq_f32_e32 v120, v120
	v_lshl_add_u64 v[118:119], v[118:119], 0, v[158:159]
	v_pk_mul_f32 v[110:111], v[110:111], v[120:121] op_sel_hi:[1,0]
	v_pk_mul_f32 v[114:115], v[114:115], v[120:121] op_sel_hi:[1,0]
	v_pk_mul_f32 v[112:113], v[112:113], v[120:121] op_sel_hi:[1,0]
	v_max_f32_e32 v110, 0, v110
	v_pk_mul_f32 v[116:117], v[116:117], v[120:121] op_sel_hi:[1,0]
	v_mul_f32_e32 v121, v110, v110
	v_max_f32_e32 v110, 0, v115
	v_max_f32_e32 v111, 0, v111
	v_max_f32_e32 v112, 0, v112
	v_max_f32_e32 v114, 0, v114
	v_mul_f32_e32 v110, v110, v110
	v_mul_f32_e32 v115, v111, v111
	v_max_f32_e32 v111, 0, v116
	v_mul_f32_e32 v116, v112, v112
	v_max_f32_e32 v112, 0, v117
	v_max_f32_e32 v113, 0, v113
	v_pk_mul_f32 v[104:105], v[104:105], v[120:121] op_sel_hi:[1,0]
	v_pk_mul_f32 v[102:103], v[102:103], v[120:121] op_sel_hi:[1,0]
	v_mul_f32_e32 v114, v114, v114
	v_mul_f32_e32 v111, v111, v111
	v_mul_f32_e32 v112, v112, v112
	v_mul_f32_e32 v113, v113, v113
	v_cvt_pk_bf16_f32 v110, v114, v110
	v_pk_mul_f32 v[108:109], v[108:109], v[120:121] op_sel_hi:[1,0]
	v_pk_mul_f32 v[106:107], v[106:107], v[120:121] op_sel_hi:[1,0]
	v_max_f32_e32 v102, 0, v102
	v_max_f32_e32 v103, 0, v103
	v_max_f32_e32 v104, 0, v104
	v_cvt_pk_bf16_f32 v111, v111, v112
	v_cvt_pk_bf16_f32 v112, v121, v115
	v_cvt_pk_bf16_f32 v113, v116, v113
	global_store_dwordx4 v[118:119], v[110:113], off
	v_max_f32_e32 v106, 0, v106
	v_max_f32_e32 v105, 0, v105
	v_mul_f32_e32 v110, v102, v102
	v_max_f32_e32 v102, 0, v107
	v_mul_f32_e32 v107, v103, v103
	v_max_f32_e32 v103, 0, v108
	v_mul_f32_e32 v108, v104, v104
	v_max_f32_e32 v104, 0, v109
	v_mul_f32_e32 v102, v102, v102
	v_mul_f32_e32 v103, v103, v103
	v_mul_f32_e32 v104, v104, v104
	v_mul_f32_e32 v106, v106, v106
	v_mul_f32_e32 v105, v105, v105
	v_cvt_pk_bf16_f32 v102, v106, v102
	v_cvt_pk_bf16_f32 v103, v103, v104
	v_cvt_pk_bf16_f32 v104, v110, v107
	v_cvt_pk_bf16_f32 v105, v108, v105
	global_store_dwordx4 v[118:119], v[102:105], off offset:256
	s_nop 1
	v_ffbh_u32_e32 v104, v161
	v_min_u32_e32 v106, 32, v104
	v_lshlrev_b64 v[104:105], v106, v[160:161]
	v_min_u32_e32 v104, 1, v104
	v_or_b32_e32 v104, v105, v104
	v_cvt_f32_u32_e32 v104, v104
	v_sub_u32_e32 v105, 32, v106
	v_lshlrev_b64 v[102:103], 14, v[162:163]
	v_lshl_add_u64 v[102:103], s[36:37], 0, v[102:103]
	v_ldexp_f32 v104, v104, v105
	v_fmamk_f32 v104, v104, 0x2e000000, v1
	v_rsq_f32_e32 v104, v104
	v_lshl_add_u64 v[102:103], v[102:103], 0, v[158:159]
	v_pk_mul_f32 v[94:95], v[94:95], v[104:105] op_sel_hi:[1,0]
	v_pk_mul_f32 v[98:99], v[98:99], v[104:105] op_sel_hi:[1,0]
	v_pk_mul_f32 v[96:97], v[96:97], v[104:105] op_sel_hi:[1,0]
	v_max_f32_e32 v94, 0, v94
	v_pk_mul_f32 v[100:101], v[100:101], v[104:105] op_sel_hi:[1,0]
	v_mul_f32_e32 v105, v94, v94
	v_max_f32_e32 v94, 0, v99
	v_max_f32_e32 v95, 0, v95
	v_max_f32_e32 v96, 0, v96
	v_max_f32_e32 v98, 0, v98
	v_mul_f32_e32 v94, v94, v94
	v_mul_f32_e32 v99, v95, v95
	v_max_f32_e32 v95, 0, v100
	v_mul_f32_e32 v100, v96, v96
	v_max_f32_e32 v96, 0, v101
	v_max_f32_e32 v97, 0, v97
	v_pk_mul_f32 v[88:89], v[88:89], v[104:105] op_sel_hi:[1,0]
	v_pk_mul_f32 v[86:87], v[86:87], v[104:105] op_sel_hi:[1,0]
	v_mul_f32_e32 v98, v98, v98
	v_mul_f32_e32 v95, v95, v95
	v_mul_f32_e32 v96, v96, v96
	v_mul_f32_e32 v97, v97, v97
	v_cvt_pk_bf16_f32 v94, v98, v94
	v_pk_mul_f32 v[92:93], v[92:93], v[104:105] op_sel_hi:[1,0]
	v_pk_mul_f32 v[90:91], v[90:91], v[104:105] op_sel_hi:[1,0]
	v_max_f32_e32 v86, 0, v86
	v_max_f32_e32 v87, 0, v87
	v_max_f32_e32 v88, 0, v88
	v_cvt_pk_bf16_f32 v95, v95, v96
	v_cvt_pk_bf16_f32 v96, v105, v99
	v_cvt_pk_bf16_f32 v97, v100, v97
	global_store_dwordx4 v[102:103], v[94:97], off
	v_max_f32_e32 v90, 0, v90
	v_max_f32_e32 v89, 0, v89
	v_mul_f32_e32 v94, v86, v86
	v_max_f32_e32 v86, 0, v91
	v_mul_f32_e32 v91, v87, v87
	v_max_f32_e32 v87, 0, v92
	v_mul_f32_e32 v92, v88, v88
	v_max_f32_e32 v88, 0, v93
	v_mul_f32_e32 v86, v86, v86
	v_mul_f32_e32 v87, v87, v87
	v_mul_f32_e32 v88, v88, v88
	v_mul_f32_e32 v90, v90, v90
	v_mul_f32_e32 v89, v89, v89
	v_cvt_pk_bf16_f32 v86, v90, v86
	v_cvt_pk_bf16_f32 v87, v87, v88
	v_cvt_pk_bf16_f32 v88, v94, v91
	v_cvt_pk_bf16_f32 v89, v92, v89
	global_store_dwordx4 v[102:103], v[86:89], off offset:256
	s_nop 1
	v_ffbh_u32_e32 v88, v155
	v_min_u32_e32 v90, 32, v88
	v_lshlrev_b64 v[88:89], v90, v[154:155]
	v_min_u32_e32 v88, 1, v88
	v_or_b32_e32 v88, v89, v88
	v_cvt_f32_u32_e32 v88, v88
	v_sub_u32_e32 v89, 32, v90
	v_lshlrev_b64 v[86:87], 14, v[156:157]
	v_lshl_add_u64 v[86:87], s[36:37], 0, v[86:87]
	v_ldexp_f32 v88, v88, v89
	v_fmamk_f32 v88, v88, 0x2e000000, v1
	v_rsq_f32_e32 v88, v88
	v_lshl_add_u64 v[86:87], v[86:87], 0, v[158:159]
	v_pk_mul_f32 v[78:79], v[78:79], v[88:89] op_sel_hi:[1,0]
	v_pk_mul_f32 v[82:83], v[82:83], v[88:89] op_sel_hi:[1,0]
	v_pk_mul_f32 v[80:81], v[80:81], v[88:89] op_sel_hi:[1,0]
	v_max_f32_e32 v78, 0, v78
	v_pk_mul_f32 v[84:85], v[84:85], v[88:89] op_sel_hi:[1,0]
	v_mul_f32_e32 v89, v78, v78
	v_max_f32_e32 v78, 0, v83
	v_max_f32_e32 v79, 0, v79
	v_max_f32_e32 v80, 0, v80
	v_max_f32_e32 v82, 0, v82
	v_mul_f32_e32 v78, v78, v78
	v_mul_f32_e32 v83, v79, v79
	v_max_f32_e32 v79, 0, v84
	v_mul_f32_e32 v84, v80, v80
	v_max_f32_e32 v80, 0, v85
	v_max_f32_e32 v81, 0, v81
	v_pk_mul_f32 v[72:73], v[72:73], v[88:89] op_sel_hi:[1,0]
	v_pk_mul_f32 v[70:71], v[70:71], v[88:89] op_sel_hi:[1,0]
	v_mul_f32_e32 v82, v82, v82
	v_mul_f32_e32 v79, v79, v79
	v_mul_f32_e32 v80, v80, v80
	v_mul_f32_e32 v81, v81, v81
	v_cvt_pk_bf16_f32 v78, v82, v78
	v_pk_mul_f32 v[76:77], v[76:77], v[88:89] op_sel_hi:[1,0]
	v_pk_mul_f32 v[74:75], v[74:75], v[88:89] op_sel_hi:[1,0]
	v_max_f32_e32 v70, 0, v70
	v_max_f32_e32 v71, 0, v71
	v_max_f32_e32 v72, 0, v72
	v_cvt_pk_bf16_f32 v79, v79, v80
	v_cvt_pk_bf16_f32 v80, v89, v83
	v_cvt_pk_bf16_f32 v81, v84, v81
	global_store_dwordx4 v[86:87], v[78:81], off
	v_max_f32_e32 v74, 0, v74
	v_max_f32_e32 v73, 0, v73
	v_mul_f32_e32 v78, v70, v70
	v_max_f32_e32 v70, 0, v75
	v_mul_f32_e32 v75, v71, v71
	v_max_f32_e32 v71, 0, v76
	v_mul_f32_e32 v76, v72, v72
	v_max_f32_e32 v72, 0, v77
	v_mul_f32_e32 v70, v70, v70
	v_mul_f32_e32 v71, v71, v71
	v_mul_f32_e32 v72, v72, v72
	v_mul_f32_e32 v74, v74, v74
	v_mul_f32_e32 v73, v73, v73
	v_cvt_pk_bf16_f32 v70, v74, v70
	v_cvt_pk_bf16_f32 v71, v71, v72
	v_cvt_pk_bf16_f32 v72, v78, v75
	v_cvt_pk_bf16_f32 v73, v76, v73
	global_store_dwordx4 v[86:87], v[70:73], off offset:256
	s_nop 1
	s_waitcnt vmcnt(8)
	v_ffbh_u32_e32 v72, v153
	v_min_u32_e32 v74, 32, v72
	v_lshlrev_b64 v[72:73], v74, v[152:153]
	v_min_u32_e32 v72, 1, v72
	v_or_b32_e32 v72, v73, v72
	v_cvt_f32_u32_e32 v72, v72
	v_sub_u32_e32 v73, 32, v74
	v_lshl_add_u64 v[70:71], v[146:147], 0, s[4:5]
	s_mov_b32 s4, 0x200000
	v_ldexp_f32 v72, v72, v73
	v_fmamk_f32 v72, v72, 0x2e000000, v1
	v_rsq_f32_e32 v72, v72
	s_nop 0
	v_pk_mul_f32 v[62:63], v[62:63], v[72:73] op_sel_hi:[1,0]
	v_pk_mul_f32 v[66:67], v[66:67], v[72:73] op_sel_hi:[1,0]
	v_pk_mul_f32 v[64:65], v[64:65], v[72:73] op_sel_hi:[1,0]
	v_max_f32_e32 v62, 0, v62
	v_pk_mul_f32 v[68:69], v[68:69], v[72:73] op_sel_hi:[1,0]
	v_max_f32_e32 v66, 0, v66
	v_mul_f32_e32 v73, v62, v62
	v_max_f32_e32 v62, 0, v67
	v_max_f32_e32 v63, 0, v63
	v_max_f32_e32 v64, 0, v64
	v_mul_f32_e32 v66, v66, v66
	v_mul_f32_e32 v62, v62, v62
	v_mul_f32_e32 v67, v63, v63
	v_max_f32_e32 v63, 0, v68
	v_mul_f32_e32 v68, v64, v64
	v_max_f32_e32 v64, 0, v69
	v_mul_f32_e32 v63, v63, v63
	v_max_f32_e32 v65, 0, v65
	v_mul_f32_e32 v64, v64, v64
	v_cvt_pk_bf16_f32 v62, v66, v62
	v_add_co_u32_e32 v66, vcc, s4, v146
	v_pk_mul_f32 v[56:57], v[56:57], v[72:73] op_sel_hi:[1,0]
	v_pk_mul_f32 v[54:55], v[54:55], v[72:73] op_sel_hi:[1,0]
	v_mul_f32_e32 v65, v65, v65
	v_cvt_pk_bf16_f32 v63, v63, v64
	v_cvt_pk_bf16_f32 v64, v73, v67
	v_addc_co_u32_e32 v67, vcc, 0, v147, vcc
	v_pk_mul_f32 v[60:61], v[60:61], v[72:73] op_sel_hi:[1,0]
	v_pk_mul_f32 v[58:59], v[58:59], v[72:73] op_sel_hi:[1,0]
	v_max_f32_e32 v54, 0, v54
	v_max_f32_e32 v55, 0, v55
	v_max_f32_e32 v56, 0, v56
	v_cvt_pk_bf16_f32 v65, v68, v65
	global_store_dwordx4 v[66:67], v[62:65], off
	v_max_f32_e32 v58, 0, v58
	v_max_f32_e32 v57, 0, v57
	v_mul_f32_e32 v62, v54, v54
	v_max_f32_e32 v54, 0, v59
	v_mul_f32_e32 v59, v55, v55
	v_max_f32_e32 v55, 0, v60
	v_mul_f32_e32 v60, v56, v56
	v_max_f32_e32 v56, 0, v61
	v_mul_f32_e32 v54, v54, v54
	v_mul_f32_e32 v55, v55, v55
	v_mul_f32_e32 v56, v56, v56
	v_mul_f32_e32 v58, v58, v58
	v_mul_f32_e32 v57, v57, v57
	v_cvt_pk_bf16_f32 v54, v58, v54
	v_cvt_pk_bf16_f32 v55, v55, v56
	v_cvt_pk_bf16_f32 v56, v62, v59
	v_cvt_pk_bf16_f32 v57, v60, v57
	global_store_dwordx4 v[70:71], v[54:57], off offset:256
	s_mov_b64 s[4:5], 0x240000
	s_nop 0
	v_ffbh_u32_e32 v56, v151
	v_min_u32_e32 v58, 32, v56
	v_lshlrev_b64 v[56:57], v58, v[150:151]
	v_min_u32_e32 v56, 1, v56
	v_or_b32_e32 v56, v57, v56
	v_cvt_f32_u32_e32 v56, v56
	v_sub_u32_e32 v57, 32, v58
	v_lshl_add_u64 v[54:55], v[146:147], 0, s[4:5]
	s_mov_b32 s4, 0x240000
	v_ldexp_f32 v56, v56, v57
	v_fmamk_f32 v56, v56, 0x2e000000, v1
	v_rsq_f32_e32 v56, v56
	s_nop 0
	v_pk_mul_f32 v[46:47], v[46:47], v[56:57] op_sel_hi:[1,0]
	v_pk_mul_f32 v[50:51], v[50:51], v[56:57] op_sel_hi:[1,0]
	v_pk_mul_f32 v[48:49], v[48:49], v[56:57] op_sel_hi:[1,0]
	v_max_f32_e32 v46, 0, v46
	v_pk_mul_f32 v[52:53], v[52:53], v[56:57] op_sel_hi:[1,0]
	v_max_f32_e32 v50, 0, v50
	v_mul_f32_e32 v57, v46, v46
	v_max_f32_e32 v46, 0, v51
	v_max_f32_e32 v47, 0, v47
	v_max_f32_e32 v48, 0, v48
	v_mul_f32_e32 v50, v50, v50
	v_mul_f32_e32 v46, v46, v46
	v_mul_f32_e32 v51, v47, v47
	v_max_f32_e32 v47, 0, v52
	v_mul_f32_e32 v52, v48, v48
	v_max_f32_e32 v48, 0, v53
	v_mul_f32_e32 v47, v47, v47
	v_max_f32_e32 v49, 0, v49
	v_mul_f32_e32 v48, v48, v48
	v_cvt_pk_bf16_f32 v46, v50, v46
	v_add_co_u32_e32 v50, vcc, s4, v146
	v_pk_mul_f32 v[40:41], v[40:41], v[56:57] op_sel_hi:[1,0]
	v_pk_mul_f32 v[38:39], v[38:39], v[56:57] op_sel_hi:[1,0]
	v_mul_f32_e32 v49, v49, v49
	v_cvt_pk_bf16_f32 v47, v47, v48
	v_cvt_pk_bf16_f32 v48, v57, v51
	v_addc_co_u32_e32 v51, vcc, 0, v147, vcc
	v_pk_mul_f32 v[44:45], v[44:45], v[56:57] op_sel_hi:[1,0]
	v_pk_mul_f32 v[42:43], v[42:43], v[56:57] op_sel_hi:[1,0]
	v_max_f32_e32 v38, 0, v38
	v_max_f32_e32 v39, 0, v39
	v_max_f32_e32 v40, 0, v40
	v_cvt_pk_bf16_f32 v49, v52, v49
	global_store_dwordx4 v[50:51], v[46:49], off
	v_max_f32_e32 v42, 0, v42
	v_max_f32_e32 v41, 0, v41
	v_mul_f32_e32 v46, v38, v38
	v_max_f32_e32 v38, 0, v43
	v_mul_f32_e32 v43, v39, v39
	v_max_f32_e32 v39, 0, v44
	v_mul_f32_e32 v44, v40, v40
	v_max_f32_e32 v40, 0, v45
	v_mul_f32_e32 v38, v38, v38
	v_mul_f32_e32 v39, v39, v39
	v_mul_f32_e32 v40, v40, v40
	v_mul_f32_e32 v42, v42, v42
	v_mul_f32_e32 v41, v41, v41
	v_cvt_pk_bf16_f32 v38, v42, v38
	v_cvt_pk_bf16_f32 v39, v39, v40
	v_cvt_pk_bf16_f32 v40, v46, v43
	v_cvt_pk_bf16_f32 v41, v44, v41
	global_store_dwordx4 v[54:55], v[38:41], off offset:256
	s_mov_b64 s[4:5], 0x280000
	s_nop 0
	v_ffbh_u32_e32 v40, v149
	v_min_u32_e32 v42, 32, v40
	v_lshlrev_b64 v[40:41], v42, v[148:149]
	v_min_u32_e32 v40, 1, v40
	v_or_b32_e32 v40, v41, v40
	v_cvt_f32_u32_e32 v40, v40
	v_sub_u32_e32 v41, 32, v42
	v_lshl_add_u64 v[38:39], v[146:147], 0, s[4:5]
	s_mov_b32 s4, 0x280000
	v_ldexp_f32 v40, v40, v41
	v_fmamk_f32 v40, v40, 0x2e000000, v1
	v_rsq_f32_e32 v40, v40
	s_nop 0
	v_pk_mul_f32 v[30:31], v[30:31], v[40:41] op_sel_hi:[1,0]
	v_pk_mul_f32 v[34:35], v[34:35], v[40:41] op_sel_hi:[1,0]
	v_pk_mul_f32 v[32:33], v[32:33], v[40:41] op_sel_hi:[1,0]
	v_max_f32_e32 v30, 0, v30
	v_pk_mul_f32 v[36:37], v[36:37], v[40:41] op_sel_hi:[1,0]
	v_max_f32_e32 v34, 0, v34
	v_mul_f32_e32 v41, v30, v30
	v_max_f32_e32 v30, 0, v35
	v_max_f32_e32 v31, 0, v31
	v_max_f32_e32 v32, 0, v32
	v_mul_f32_e32 v34, v34, v34
	v_mul_f32_e32 v30, v30, v30
	v_mul_f32_e32 v35, v31, v31
	v_max_f32_e32 v31, 0, v36
	v_mul_f32_e32 v36, v32, v32
	v_max_f32_e32 v32, 0, v37
	v_mul_f32_e32 v31, v31, v31
	v_max_f32_e32 v33, 0, v33
	v_mul_f32_e32 v32, v32, v32
	v_cvt_pk_bf16_f32 v30, v34, v30
	v_add_co_u32_e32 v34, vcc, s4, v146
	v_pk_mul_f32 v[24:25], v[24:25], v[40:41] op_sel_hi:[1,0]
	v_pk_mul_f32 v[22:23], v[22:23], v[40:41] op_sel_hi:[1,0]
	v_mul_f32_e32 v33, v33, v33
	v_cvt_pk_bf16_f32 v31, v31, v32
	v_cvt_pk_bf16_f32 v32, v41, v35
	v_addc_co_u32_e32 v35, vcc, 0, v147, vcc
	v_pk_mul_f32 v[28:29], v[28:29], v[40:41] op_sel_hi:[1,0]
	v_pk_mul_f32 v[26:27], v[26:27], v[40:41] op_sel_hi:[1,0]
	v_max_f32_e32 v22, 0, v22
	v_max_f32_e32 v23, 0, v23
	v_max_f32_e32 v24, 0, v24
	v_cvt_pk_bf16_f32 v33, v36, v33
	global_store_dwordx4 v[34:35], v[30:33], off
	v_max_f32_e32 v26, 0, v26
	v_max_f32_e32 v25, 0, v25
	v_mul_f32_e32 v30, v22, v22
	v_max_f32_e32 v22, 0, v27
	v_mul_f32_e32 v27, v23, v23
	v_max_f32_e32 v23, 0, v28
	v_mul_f32_e32 v28, v24, v24
	v_max_f32_e32 v24, 0, v29
	v_mul_f32_e32 v22, v22, v22
	v_mul_f32_e32 v23, v23, v23
	v_mul_f32_e32 v24, v24, v24
	v_mul_f32_e32 v26, v26, v26
	v_mul_f32_e32 v25, v25, v25
	v_cvt_pk_bf16_f32 v22, v26, v22
	v_cvt_pk_bf16_f32 v23, v23, v24
	v_cvt_pk_bf16_f32 v24, v30, v27
	v_cvt_pk_bf16_f32 v25, v28, v25
	global_store_dwordx4 v[38:39], v[22:25], off offset:256
	s_mov_b64 s[4:5], 0x2c0000
	s_nop 0
	v_ffbh_u32_e32 v24, v145
	v_min_u32_e32 v26, 32, v24
	v_lshlrev_b64 v[24:25], v26, v[144:145]
	v_min_u32_e32 v24, 1, v24
	v_or_b32_e32 v24, v25, v24
	v_cvt_f32_u32_e32 v24, v24
	v_sub_u32_e32 v25, 32, v26
	v_lshl_add_u64 v[22:23], v[146:147], 0, s[4:5]
	s_mov_b32 s4, 0x2c0000
	v_ldexp_f32 v24, v24, v25
	v_fmamk_f32 v24, v24, 0x2e000000, v1
	v_rsq_f32_e32 v24, v24
	s_nop 0
	v_pk_mul_f32 v[14:15], v[14:15], v[24:25] op_sel_hi:[1,0]
	v_pk_mul_f32 v[18:19], v[18:19], v[24:25] op_sel_hi:[1,0]
	v_pk_mul_f32 v[16:17], v[16:17], v[24:25] op_sel_hi:[1,0]
	v_max_f32_e32 v14, 0, v14
	v_pk_mul_f32 v[20:21], v[20:21], v[24:25] op_sel_hi:[1,0]
	v_max_f32_e32 v18, 0, v18
	v_mul_f32_e32 v25, v14, v14
	v_max_f32_e32 v14, 0, v19
	v_max_f32_e32 v15, 0, v15
	v_max_f32_e32 v16, 0, v16
	v_mul_f32_e32 v18, v18, v18
	v_mul_f32_e32 v14, v14, v14
	v_mul_f32_e32 v19, v15, v15
	v_max_f32_e32 v15, 0, v20
	v_mul_f32_e32 v20, v16, v16
	v_max_f32_e32 v16, 0, v21
	v_mul_f32_e32 v15, v15, v15
	v_max_f32_e32 v17, 0, v17
	v_mul_f32_e32 v16, v16, v16
	v_cvt_pk_bf16_f32 v14, v18, v14
	v_add_co_u32_e32 v18, vcc, s4, v146
	v_pk_mul_f32 v[8:9], v[8:9], v[24:25] op_sel_hi:[1,0]
	v_pk_mul_f32 v[6:7], v[6:7], v[24:25] op_sel_hi:[1,0]
	v_mul_f32_e32 v17, v17, v17
	v_cvt_pk_bf16_f32 v15, v15, v16
	v_cvt_pk_bf16_f32 v16, v25, v19
	v_addc_co_u32_e32 v19, vcc, 0, v147, vcc
	v_pk_mul_f32 v[12:13], v[12:13], v[24:25] op_sel_hi:[1,0]
	v_pk_mul_f32 v[10:11], v[10:11], v[24:25] op_sel_hi:[1,0]
	v_max_f32_e32 v6, 0, v6
	v_max_f32_e32 v7, 0, v7
	v_max_f32_e32 v8, 0, v8
	v_cvt_pk_bf16_f32 v17, v20, v17
	global_store_dwordx4 v[18:19], v[14:17], off
	v_max_f32_e32 v9, 0, v9
	v_max_f32_e32 v10, 0, v10
	v_mul_f32_e32 v14, v6, v6
	v_max_f32_e32 v6, 0, v11
	v_mul_f32_e32 v11, v7, v7
	v_max_f32_e32 v7, 0, v12
	v_mul_f32_e32 v12, v8, v8
	v_max_f32_e32 v8, 0, v13
	v_mul_f32_e32 v6, v6, v6
	v_mul_f32_e32 v7, v7, v7
	v_mul_f32_e32 v8, v8, v8
	v_mul_f32_e32 v9, v9, v9
	s_mov_b64 s[4:5], -1
	s_andn2_b64 vcc, exec, s[38:39]
	v_mul_f32_e32 v10, v10, v10
	v_cvt_pk_bf16_f32 v6, v10, v6
	v_cvt_pk_bf16_f32 v7, v7, v8
	v_cvt_pk_bf16_f32 v8, v14, v11
	v_cvt_pk_bf16_f32 v9, v12, v9
	global_store_dwordx4 v[22:23], v[6:9], off offset:256
	s_cbranch_vccnz .LBB0_72
	s_andn2_b64 vcc, exec, s[18:19]
	s_cbranch_vccnz .LBB0_71
	s_barrier
	s_branch .LBB0_71

.LBB0_1053:
	s_ashr_i32 s47, s46, 31
	s_lshl_b64 s[4:5], s[46:47], 20
	v_readlane_b32 s50, v255, 14
	v_readlane_b32 s51, v255, 15
	s_add_u32 s50, s50, s4
	s_addc_u32 s51, s51, s5
	s_and_b64 s[4:5], s[38:39], exec
	s_cselect_b32 s4, s51, s59
	s_cselect_b32 s5, s50, s58
	s_ashr_i32 s45, s44, 31
	s_lshl_b64 s[52:53], s[44:45], 20
	s_add_u32 s52, s48, s52
	s_addc_u32 s53, s49, s53
	s_and_b64 s[60:61], s[38:39], exec
	s_cselect_b32 s45, s53, s57
	s_cselect_b32 s47, s52, s56
	s_add_u32 s62, s56, 0x100
	s_addc_u32 s63, s57, 0
	s_add_u32 s56, s58, 0x80080
	v_mov_b32_e32 v6, 0
	s_addc_u32 s57, s59, 0
	s_mov_b32 s64, -2
	v_mov_b32_e32 v7, v6
	v_mov_b32_e32 v8, v6
	v_mov_b32_e32 v9, v6
	v_mov_b32_e32 v10, v6
	v_mov_b32_e32 v11, v6
	v_mov_b32_e32 v12, v6
	v_mov_b32_e32 v13, v6
	v_mov_b32_e32 v22, v6
	v_mov_b32_e32 v23, v6
	v_mov_b32_e32 v24, v6
	v_mov_b32_e32 v25, v6
	v_mov_b32_e32 v26, v6
	v_mov_b32_e32 v27, v6
	v_mov_b32_e32 v28, v6
	v_mov_b32_e32 v29, v6
	v_mov_b32_e32 v38, v6
	v_mov_b32_e32 v39, v6
	v_mov_b32_e32 v40, v6
	v_mov_b32_e32 v41, v6
	s_waitcnt vmcnt(0)
	v_mov_b32_e32 v42, v6
	v_mov_b32_e32 v43, v6
	v_mov_b32_e32 v44, v6
	v_mov_b32_e32 v45, v6
	v_mov_b32_e32 v54, v6
	v_mov_b32_e32 v55, v6
	v_mov_b32_e32 v56, v6
	v_mov_b32_e32 v57, v6
	v_mov_b32_e32 v58, v6
	v_mov_b32_e32 v59, v6
	v_mov_b32_e32 v60, v6
	v_mov_b32_e32 v61, v6
	v_mov_b32_e32 v14, v6
	v_mov_b32_e32 v15, v6
	v_mov_b32_e32 v16, v6
	v_mov_b32_e32 v17, v6
	v_mov_b32_e32 v18, v6
	v_mov_b32_e32 v19, v6
	v_mov_b32_e32 v20, v6
	v_mov_b32_e32 v21, v6
	v_mov_b32_e32 v30, v6
	v_mov_b32_e32 v31, v6
	v_mov_b32_e32 v32, v6
	v_mov_b32_e32 v33, v6
	v_mov_b32_e32 v34, v6
	v_mov_b32_e32 v35, v6
	v_mov_b32_e32 v36, v6
	v_mov_b32_e32 v37, v6
	v_mov_b32_e32 v46, v6
	v_mov_b32_e32 v47, v6
	v_mov_b32_e32 v48, v6
	v_mov_b32_e32 v49, v6
	v_mov_b32_e32 v50, v6
	v_mov_b32_e32 v51, v6
	v_mov_b32_e32 v52, v6
	v_mov_b32_e32 v53, v6
	v_mov_b32_e32 v62, v6
	v_mov_b32_e32 v63, v6
	v_mov_b32_e32 v64, v6
	v_mov_b32_e32 v65, v6
	v_mov_b32_e32 v66, v6
	v_mov_b32_e32 v67, v6
	v_mov_b32_e32 v68, v6
	v_mov_b32_e32 v69, v6
	v_mov_b32_e32 v70, v6
	v_mov_b32_e32 v71, v6
	v_mov_b32_e32 v72, v6
	v_mov_b32_e32 v73, v6
	v_mov_b32_e32 v74, v6
	v_mov_b32_e32 v75, v6
	v_mov_b32_e32 v76, v6
	v_mov_b32_e32 v77, v6
	v_mov_b32_e32 v86, v6
	v_mov_b32_e32 v87, v6
	v_mov_b32_e32 v88, v6
	v_mov_b32_e32 v89, v6
	v_mov_b32_e32 v90, v6
	v_mov_b32_e32 v91, v6
	v_mov_b32_e32 v92, v6
	v_mov_b32_e32 v93, v6
	v_mov_b32_e32 v102, v6
	v_mov_b32_e32 v103, v6
	v_mov_b32_e32 v104, v6
	v_mov_b32_e32 v105, v6
	v_mov_b32_e32 v106, v6
	v_mov_b32_e32 v107, v6
	v_mov_b32_e32 v108, v6
	v_mov_b32_e32 v109, v6
	v_mov_b32_e32 v118, v6
	v_mov_b32_e32 v119, v6
	v_mov_b32_e32 v120, v6
	v_mov_b32_e32 v121, v6
	v_mov_b32_e32 v122, v6
	v_mov_b32_e32 v123, v6
	v_mov_b32_e32 v124, v6
	v_mov_b32_e32 v125, v6
	v_mov_b32_e32 v78, v6
	v_mov_b32_e32 v79, v6
	v_mov_b32_e32 v80, v6
	v_mov_b32_e32 v81, v6
	v_mov_b32_e32 v82, v6
	v_mov_b32_e32 v83, v6
	v_mov_b32_e32 v84, v6
	v_mov_b32_e32 v85, v6
	v_mov_b32_e32 v94, v6
	v_mov_b32_e32 v95, v6
	v_mov_b32_e32 v96, v6
	v_mov_b32_e32 v97, v6
	v_mov_b32_e32 v98, v6
	v_mov_b32_e32 v99, v6
	v_mov_b32_e32 v100, v6
	v_mov_b32_e32 v101, v6
	v_mov_b32_e32 v110, v6
	v_mov_b32_e32 v111, v6
	v_mov_b32_e32 v112, v6
	v_mov_b32_e32 v113, v6
	v_mov_b32_e32 v114, v6
	v_mov_b32_e32 v115, v6
	v_mov_b32_e32 v116, v6
	v_mov_b32_e32 v117, v6
	v_mov_b32_e32 v126, v6
	v_mov_b32_e32 v127, v6
	v_mov_b32_e32 v128, v6
	v_mov_b32_e32 v129, v6
	v_mov_b32_e32 v130, v6
	v_mov_b32_e32 v131, v6
	v_mov_b32_e32 v132, v6
	v_mov_b32_e32 v133, v6
	v_lshl_add_u32 v2, s54, 8, v162
	v_ashrrev_i32_e32 v3, 31, v2
	v_lshl_add_u64 v[2:3], v[2:3], 3, s[40:41]
	global_load_dwordx2 v[246:247], v[2:3], off
	global_load_dwordx2 v[248:249], v[2:3], off offset:128
	global_load_dwordx2 v[250:251], v[2:3], off offset:256
	global_load_dwordx2 v[252:253], v[2:3], off offset:384
	s_nop 1
	v_mov_b32_e32 v2, 0
	v_mov_b32_e32 v3, 0

.LBB0_1057:
	v_lshl_add_u32 v150, s54, 8, v162
	v_ashrrev_i32_e32 v151, 31, v150
	v_lshl_add_u64 v[144:145], v[150:151], 3, s[40:41]
	v_mov_b64_e32 v[172:173], v[246:247]
	v_mov_b64_e32 v[160:161], v[248:249]
	v_mov_b64_e32 v[158:159], v[250:251]
	v_mov_b64_e32 v[156:157], v[252:253]
	global_load_dwordx2 v[154:155], v[144:145], off offset:1024
	global_load_dwordx2 v[152:153], v[144:145], off offset:1152
	global_load_dwordx2 v[148:149], v[144:145], off offset:1280
	v_lshl_or_b32 v174, s55, 8, v164
	v_ashrrev_i32_e32 v175, 31, v174
	v_mov_b64_e32 v[146:147], s[36:37]
	v_or_b32_e32 v171, 16, v150
	v_or_b32_e32 v178, 32, v150
	v_or_b32_e32 v170, 48, v150
	v_add_u32_e32 v169, 0x80, v150
	v_add_u32_e32 v168, 0x90, v150
	v_add_u32_e32 v167, 0xa0, v150
	v_add_u32_e32 v166, 0xb0, v150
	v_mad_i64_i32 v[176:177], s[4:5], v150, s9, v[146:147]
	v_lshlrev_b64 v[150:151], 1, v[174:175]
	v_lshl_add_u64 v[174:175], v[176:177], 0, v[150:151]
	global_load_dwordx2 v[144:145], v[144:145], off offset:1408
	s_andn2_b64 vcc, exec, s[38:39]
	v_ffbh_u32_e32 v176, v173
	v_min_u32_e32 v176, 32, v176
	v_lshlrev_b64 v[172:173], v176, v[172:173]
	v_min_u32_e32 v172, 1, v172
	v_or_b32_e32 v172, v173, v172
	v_cvt_f32_u32_e32 v172, v172
	v_sub_u32_e32 v173, 32, v176
	v_ldexp_f32 v172, v172, v173
	v_fmamk_f32 v172, v172, 0x2e000000, v1
	v_rsq_f32_e32 v172, v172
	s_nop 0
	v_pk_mul_f32 v[132:133], v[132:133], v[172:173] op_sel_hi:[1,0]
	v_pk_mul_f32 v[130:131], v[130:131], v[172:173] op_sel_hi:[1,0]
	v_pk_mul_f32 v[176:177], v[128:129], v[172:173] op_sel_hi:[1,0]
	v_pk_mul_f32 v[128:129], v[126:127], v[172:173] op_sel_hi:[1,0]
	v_cvt_pk_bf16_f32 v126, v130, v131
	v_cvt_pk_bf16_f32 v127, v132, v133
	v_pk_mul_f32 v[124:125], v[124:125], v[172:173] op_sel_hi:[1,0]
	v_cvt_pk_bf16_f32 v128, v128, v129
	v_cvt_pk_bf16_f32 v129, v176, v177
	global_store_dwordx4 v[174:175], v[126:129], off
	v_pk_mul_f32 v[122:123], v[122:123], v[172:173] op_sel_hi:[1,0]
	s_nop 0
	v_pk_mul_f32 v[126:127], v[120:121], v[172:173] op_sel_hi:[1,0]
	v_pk_mul_f32 v[120:121], v[118:119], v[172:173] op_sel_hi:[1,0]
	v_cvt_pk_bf16_f32 v118, v122, v123
	v_cvt_pk_bf16_f32 v119, v124, v125
	s_nop 0
	v_cvt_pk_bf16_f32 v120, v120, v121
	v_cvt_pk_bf16_f32 v121, v126, v127
	global_store_dwordx4 v[174:175], v[118:121], off offset:256
	s_nop 1
	v_ffbh_u32_e32 v120, v161
	v_min_u32_e32 v122, 32, v120
	v_lshlrev_b64 v[120:121], v122, v[160:161]
	v_min_u32_e32 v120, 1, v120
	v_or_b32_e32 v120, v121, v120
	v_cvt_f32_u32_e32 v120, v120
	v_sub_u32_e32 v121, 32, v122
	v_mad_i64_i32 v[118:119], s[4:5], v171, s9, v[146:147]
	v_ldexp_f32 v120, v120, v121
	v_fmamk_f32 v120, v120, 0x2e000000, v1
	v_rsq_f32_e32 v120, v120
	v_lshl_add_u64 v[118:119], v[118:119], 0, v[150:151]
	v_pk_mul_f32 v[116:117], v[116:117], v[120:121] op_sel_hi:[1,0]
	v_pk_mul_f32 v[114:115], v[114:115], v[120:121] op_sel_hi:[1,0]
	v_pk_mul_f32 v[122:123], v[112:113], v[120:121] op_sel_hi:[1,0]
	v_pk_mul_f32 v[112:113], v[110:111], v[120:121] op_sel_hi:[1,0]
	v_cvt_pk_bf16_f32 v110, v114, v115
	v_cvt_pk_bf16_f32 v111, v116, v117
	v_pk_mul_f32 v[108:109], v[108:109], v[120:121] op_sel_hi:[1,0]
	v_cvt_pk_bf16_f32 v112, v112, v113
	v_cvt_pk_bf16_f32 v113, v122, v123
	global_store_dwordx4 v[118:119], v[110:113], off
	v_pk_mul_f32 v[106:107], v[106:107], v[120:121] op_sel_hi:[1,0]
	s_nop 0
	v_pk_mul_f32 v[110:111], v[104:105], v[120:121] op_sel_hi:[1,0]
	v_pk_mul_f32 v[104:105], v[102:103], v[120:121] op_sel_hi:[1,0]
	v_cvt_pk_bf16_f32 v102, v106, v107
	v_cvt_pk_bf16_f32 v103, v108, v109
	s_nop 0
	v_cvt_pk_bf16_f32 v104, v104, v105
	v_cvt_pk_bf16_f32 v105, v110, v111
	global_store_dwordx4 v[118:119], v[102:105], off offset:256
	s_nop 1
	v_ffbh_u32_e32 v104, v159
	v_min_u32_e32 v106, 32, v104
	v_lshlrev_b64 v[104:105], v106, v[158:159]
	v_min_u32_e32 v104, 1, v104
	v_or_b32_e32 v104, v105, v104
	v_cvt_f32_u32_e32 v104, v104
	v_sub_u32_e32 v105, 32, v106
	v_mad_i64_i32 v[102:103], s[4:5], v178, s9, v[146:147]
	v_ldexp_f32 v104, v104, v105
	v_fmamk_f32 v104, v104, 0x2e000000, v1
	v_rsq_f32_e32 v104, v104
	v_lshl_add_u64 v[102:103], v[102:103], 0, v[150:151]
	v_pk_mul_f32 v[100:101], v[100:101], v[104:105] op_sel_hi:[1,0]
	v_pk_mul_f32 v[98:99], v[98:99], v[104:105] op_sel_hi:[1,0]
	v_pk_mul_f32 v[106:107], v[96:97], v[104:105] op_sel_hi:[1,0]
	v_pk_mul_f32 v[96:97], v[94:95], v[104:105] op_sel_hi:[1,0]
	v_cvt_pk_bf16_f32 v94, v98, v99
	v_cvt_pk_bf16_f32 v95, v100, v101
	v_pk_mul_f32 v[92:93], v[92:93], v[104:105] op_sel_hi:[1,0]
	v_cvt_pk_bf16_f32 v96, v96, v97
	v_cvt_pk_bf16_f32 v97, v106, v107
	global_store_dwordx4 v[102:103], v[94:97], off
	v_pk_mul_f32 v[90:91], v[90:91], v[104:105] op_sel_hi:[1,0]
	s_nop 0
	v_pk_mul_f32 v[94:95], v[88:89], v[104:105] op_sel_hi:[1,0]
	v_pk_mul_f32 v[88:89], v[86:87], v[104:105] op_sel_hi:[1,0]
	v_cvt_pk_bf16_f32 v86, v90, v91
	v_cvt_pk_bf16_f32 v87, v92, v93
	s_nop 0
	v_cvt_pk_bf16_f32 v88, v88, v89
	v_cvt_pk_bf16_f32 v89, v94, v95
	global_store_dwordx4 v[102:103], v[86:89], off offset:256
	s_nop 1
	v_ffbh_u32_e32 v88, v157
	v_min_u32_e32 v90, 32, v88
	v_lshlrev_b64 v[88:89], v90, v[156:157]
	v_min_u32_e32 v88, 1, v88
	v_or_b32_e32 v88, v89, v88
	v_cvt_f32_u32_e32 v88, v88
	v_sub_u32_e32 v89, 32, v90
	v_mad_i64_i32 v[86:87], s[4:5], v170, s9, v[146:147]
	v_ldexp_f32 v88, v88, v89
	v_fmamk_f32 v88, v88, 0x2e000000, v1
	v_rsq_f32_e32 v88, v88
	v_lshl_add_u64 v[86:87], v[86:87], 0, v[150:151]
	v_pk_mul_f32 v[84:85], v[84:85], v[88:89] op_sel_hi:[1,0]
	v_pk_mul_f32 v[82:83], v[82:83], v[88:89] op_sel_hi:[1,0]
	v_pk_mul_f32 v[90:91], v[80:81], v[88:89] op_sel_hi:[1,0]
	v_pk_mul_f32 v[80:81], v[78:79], v[88:89] op_sel_hi:[1,0]
	v_cvt_pk_bf16_f32 v78, v82, v83
	v_cvt_pk_bf16_f32 v79, v84, v85
	v_pk_mul_f32 v[76:77], v[76:77], v[88:89] op_sel_hi:[1,0]
	v_cvt_pk_bf16_f32 v80, v80, v81
	v_cvt_pk_bf16_f32 v81, v90, v91
	global_store_dwordx4 v[86:87], v[78:81], off
	v_pk_mul_f32 v[74:75], v[74:75], v[88:89] op_sel_hi:[1,0]
	s_nop 0
	v_pk_mul_f32 v[78:79], v[72:73], v[88:89] op_sel_hi:[1,0]
	v_pk_mul_f32 v[72:73], v[70:71], v[88:89] op_sel_hi:[1,0]
	v_cvt_pk_bf16_f32 v70, v74, v75
	v_cvt_pk_bf16_f32 v71, v76, v77
	s_nop 0
	v_cvt_pk_bf16_f32 v72, v72, v73
	v_cvt_pk_bf16_f32 v73, v78, v79
	global_store_dwordx4 v[86:87], v[70:73], off offset:256
	s_nop 1
	s_waitcnt vmcnt(8)
	v_ffbh_u32_e32 v72, v155
	v_min_u32_e32 v74, 32, v72
	v_lshlrev_b64 v[72:73], v74, v[154:155]
	v_min_u32_e32 v72, 1, v72
	v_or_b32_e32 v72, v73, v72
	v_cvt_f32_u32_e32 v72, v72
	v_sub_u32_e32 v73, 32, v74
	v_mad_i64_i32 v[70:71], s[4:5], v169, s9, v[146:147]
	v_ldexp_f32 v72, v72, v73
	v_fmamk_f32 v72, v72, 0x2e000000, v1
	v_rsq_f32_e32 v72, v72
	v_lshl_add_u64 v[70:71], v[70:71], 0, v[150:151]
	v_pk_mul_f32 v[68:69], v[68:69], v[72:73] op_sel_hi:[1,0]
	v_pk_mul_f32 v[66:67], v[66:67], v[72:73] op_sel_hi:[1,0]
	v_pk_mul_f32 v[74:75], v[64:65], v[72:73] op_sel_hi:[1,0]
	v_pk_mul_f32 v[64:65], v[62:63], v[72:73] op_sel_hi:[1,0]
	v_cvt_pk_bf16_f32 v62, v66, v67
	v_cvt_pk_bf16_f32 v63, v68, v69
	v_pk_mul_f32 v[60:61], v[60:61], v[72:73] op_sel_hi:[1,0]
	v_cvt_pk_bf16_f32 v64, v64, v65
	v_cvt_pk_bf16_f32 v65, v74, v75
	global_store_dwordx4 v[70:71], v[62:65], off
	v_pk_mul_f32 v[58:59], v[58:59], v[72:73] op_sel_hi:[1,0]
	s_nop 0
	v_pk_mul_f32 v[62:63], v[56:57], v[72:73] op_sel_hi:[1,0]
	v_pk_mul_f32 v[56:57], v[54:55], v[72:73] op_sel_hi:[1,0]
	v_cvt_pk_bf16_f32 v54, v58, v59
	v_cvt_pk_bf16_f32 v55, v60, v61
	s_nop 0
	v_cvt_pk_bf16_f32 v56, v56, v57
	v_cvt_pk_bf16_f32 v57, v62, v63
	global_store_dwordx4 v[70:71], v[54:57], off offset:256
	s_nop 1
	v_ffbh_u32_e32 v56, v153
	v_min_u32_e32 v58, 32, v56
	v_lshlrev_b64 v[56:57], v58, v[152:153]
	v_min_u32_e32 v56, 1, v56
	v_or_b32_e32 v56, v57, v56
	v_cvt_f32_u32_e32 v56, v56
	v_sub_u32_e32 v57, 32, v58
	v_mad_i64_i32 v[54:55], s[4:5], v168, s9, v[146:147]
	v_ldexp_f32 v56, v56, v57
	v_fmamk_f32 v56, v56, 0x2e000000, v1
	v_rsq_f32_e32 v56, v56
	v_lshl_add_u64 v[54:55], v[54:55], 0, v[150:151]
	v_pk_mul_f32 v[52:53], v[52:53], v[56:57] op_sel_hi:[1,0]
	v_pk_mul_f32 v[50:51], v[50:51], v[56:57] op_sel_hi:[1,0]
	v_pk_mul_f32 v[58:59], v[48:49], v[56:57] op_sel_hi:[1,0]
	v_pk_mul_f32 v[48:49], v[46:47], v[56:57] op_sel_hi:[1,0]
	v_cvt_pk_bf16_f32 v46, v50, v51
	v_cvt_pk_bf16_f32 v47, v52, v53
	v_pk_mul_f32 v[44:45], v[44:45], v[56:57] op_sel_hi:[1,0]
	v_cvt_pk_bf16_f32 v48, v48, v49
	v_cvt_pk_bf16_f32 v49, v58, v59
	global_store_dwordx4 v[54:55], v[46:49], off
	v_pk_mul_f32 v[42:43], v[42:43], v[56:57] op_sel_hi:[1,0]
	s_nop 0
	v_pk_mul_f32 v[46:47], v[40:41], v[56:57] op_sel_hi:[1,0]
	v_pk_mul_f32 v[40:41], v[38:39], v[56:57] op_sel_hi:[1,0]
	v_cvt_pk_bf16_f32 v38, v42, v43
	v_cvt_pk_bf16_f32 v39, v44, v45
	s_nop 0
	v_cvt_pk_bf16_f32 v40, v40, v41
	v_cvt_pk_bf16_f32 v41, v46, v47
	global_store_dwordx4 v[54:55], v[38:41], off offset:256
	s_nop 1
	v_ffbh_u32_e32 v40, v149
	v_min_u32_e32 v42, 32, v40
	v_lshlrev_b64 v[40:41], v42, v[148:149]
	v_min_u32_e32 v40, 1, v40
	v_or_b32_e32 v40, v41, v40
	v_cvt_f32_u32_e32 v40, v40
	v_sub_u32_e32 v41, 32, v42
	v_mad_i64_i32 v[38:39], s[4:5], v167, s9, v[146:147]
	v_ldexp_f32 v40, v40, v41
	v_fmamk_f32 v40, v40, 0x2e000000, v1
	v_rsq_f32_e32 v40, v40
	v_lshl_add_u64 v[38:39], v[38:39], 0, v[150:151]
	v_pk_mul_f32 v[36:37], v[36:37], v[40:41] op_sel_hi:[1,0]
	v_pk_mul_f32 v[34:35], v[34:35], v[40:41] op_sel_hi:[1,0]
	v_pk_mul_f32 v[42:43], v[32:33], v[40:41] op_sel_hi:[1,0]
	v_pk_mul_f32 v[32:33], v[30:31], v[40:41] op_sel_hi:[1,0]
	v_cvt_pk_bf16_f32 v30, v34, v35
	v_cvt_pk_bf16_f32 v31, v36, v37
	v_pk_mul_f32 v[28:29], v[28:29], v[40:41] op_sel_hi:[1,0]
	v_cvt_pk_bf16_f32 v32, v32, v33
	v_cvt_pk_bf16_f32 v33, v42, v43
	global_store_dwordx4 v[38:39], v[30:33], off
	v_pk_mul_f32 v[26:27], v[26:27], v[40:41] op_sel_hi:[1,0]
	s_nop 0
	v_pk_mul_f32 v[30:31], v[24:25], v[40:41] op_sel_hi:[1,0]
	v_pk_mul_f32 v[24:25], v[22:23], v[40:41] op_sel_hi:[1,0]
	v_cvt_pk_bf16_f32 v22, v26, v27
	v_cvt_pk_bf16_f32 v23, v28, v29
	s_nop 0
	v_cvt_pk_bf16_f32 v24, v24, v25
	v_cvt_pk_bf16_f32 v25, v30, v31
	global_store_dwordx4 v[38:39], v[22:25], off offset:256
	s_nop 1
	v_ffbh_u32_e32 v24, v145
	v_min_u32_e32 v26, 32, v24
	v_lshlrev_b64 v[24:25], v26, v[144:145]
	v_min_u32_e32 v24, 1, v24
	v_or_b32_e32 v24, v25, v24
	v_cvt_f32_u32_e32 v24, v24
	v_sub_u32_e32 v25, 32, v26
	v_mad_i64_i32 v[22:23], s[4:5], v166, s9, v[146:147]
	v_ldexp_f32 v24, v24, v25
	v_fmamk_f32 v24, v24, 0x2e000000, v1
	v_rsq_f32_e32 v24, v24
	v_lshl_add_u64 v[22:23], v[22:23], 0, v[150:151]
	s_mov_b64 s[4:5], -1
	v_pk_mul_f32 v[20:21], v[20:21], v[24:25] op_sel_hi:[1,0]
	v_pk_mul_f32 v[18:19], v[18:19], v[24:25] op_sel_hi:[1,0]
	v_pk_mul_f32 v[26:27], v[16:17], v[24:25] op_sel_hi:[1,0]
	v_pk_mul_f32 v[16:17], v[14:15], v[24:25] op_sel_hi:[1,0]
	v_cvt_pk_bf16_f32 v14, v18, v19
	v_cvt_pk_bf16_f32 v15, v20, v21
	v_pk_mul_f32 v[12:13], v[12:13], v[24:25] op_sel_hi:[1,0]
	v_cvt_pk_bf16_f32 v16, v16, v17
	v_cvt_pk_bf16_f32 v17, v26, v27
	global_store_dwordx4 v[22:23], v[14:17], off
	v_pk_mul_f32 v[10:11], v[10:11], v[24:25] op_sel_hi:[1,0]
	s_nop 0
	v_pk_mul_f32 v[14:15], v[8:9], v[24:25] op_sel_hi:[1,0]
	v_pk_mul_f32 v[8:9], v[6:7], v[24:25] op_sel_hi:[1,0]
	v_cvt_pk_bf16_f32 v6, v10, v11
	v_cvt_pk_bf16_f32 v7, v12, v13
	s_nop 0
	v_cvt_pk_bf16_f32 v8, v8, v9
	v_cvt_pk_bf16_f32 v9, v14, v15
	global_store_dwordx4 v[22:23], v[6:9], off offset:256
	s_cbranch_vccnz .LBB0_1050
	s_andn2_b64 vcc, exec, s[18:19]
	s_cbranch_vccnz .LBB0_1049
	s_barrier
	s_branch .LBB0_1049
